# attention K tile LDS swizzle (row&15)<<4 instead of (row&7)<<4: conflict-free ds_read_b128 K reads
# speedup vs baseline: 1.0005x; 1.0005x over previous
; template <bool MLA> ...
;     ...
;   const int tid = opaque_tid(), wid = __builtin_amdgcn_readfirstlane(tid >> 6), lane = tid & 63, r32 = lane & 31, hi = lane >> 5;
;   char* V_lds = lds + OFF_V; char* K_lds = lds + OFF_K; char* KR_lds = lds + OFF_KR;
;   float* ws = (float*)(lds + OFF_WS) + wid * 64; float* li_l = ws; float* al_l = ws + 32;
;   unsigned koff[2], voff[2], kroff = 0;
; #pragma unroll
;   for (int i = 0; i < 2; ++i) { const int p = 2 * wid + i;
;     { const int row = 4 * p + (lane >> 4), pc = lane & 15, c = pc ^ (row & 7); koff[i] = (unsigned)(row * LDK + c * 8) * 2u; }
;     { const int o = p * 1024 + lane * 16, sub = o >> 9, w_ = (o & 511) >> 1, kk = (sub >> 2) * 8 + (w_ >> 5), k = (kk & ~0xC) | ((kk & 4) << 1) | ((kk & 8) >> 1), c = (sub & 3) * 32 + (w_ & 31);
;       voff[i] = (unsigned)(k * LDK + c) * 2u; } }
;   if constexpr (MLA) { const int row = 8 * wid + (lane >> 3), pc = lane & 7, ch = pc ^ ((row >> 1) & 7); kroff = (unsigned)(row * LDKR + ch * 8) * 2u; }
;     ...
;   DMA_TILE(0, 0); DMA_TILE(1, 1);
;   float l_reg = 0, m_reg = 0; f32x16 o[4] = {}; bf16x8 qr[8]; f32x16 negm = {}; asm volatile("" : "+v"(negm));
;   char* qrl = lds + OFF_QR + wid * 4096 + lane * 16;
;   { const bf16_t* Qw = Qb + (long)(wid * QBLK + r32) * LDQ + hi * 8;
; #pragma unroll
;     for (int d0 = 0; d0 < 8; ++d0) qr[d0] = *reinterpret_cast<const bf16x8*>(Qw + d0 * 16);
;     if constexpr (MLA) { const bf16_t* Qw2 = Qrb + (long)(wid * QBLK + r32) * LDQ + hi * 8;
; #pragma unroll
;       for (int d0 = 0; d0 < 4; ++d0) *reinterpret_cast<bf16x8*>(qrl + d0 * 1024) = *reinterpret_cast<const bf16x8*>(Qw2 + d0 * 16); } }
;   const int vb0 = (int)(uintptr_t)V_lds + v_rd_base(lane);
;     ...
;   f32x16 pA0, pA1, pB0, pB1; float alA, alB; bf16x8 pa0, pa1, pa2, pa3;
;   WAIT_BAR();
; __global__ void __launch_bounds__(512) mega_fwd(Params p) {
;     ...
;                 const int mla = u / 1536, v = u % 1536, grp = v >> 8, w = v & 255, bh = grp * 8 + (w & 7), qb = w >> 3, b = bh >> 3, h = bh & 7;
;                 const size_t row0 = (size_t)b * SEQ, q0 = row0 + (size_t)qb * 256;
;                 if (!mla) {
;                     att::attn_unit<false>(QQ + q0 * LDQQ + h * 128, nullptr, QQ + row0 * LDQQ + 2560 + (h >> 2) * 128, nullptr, QQ + row0 * LDQQ + 2816 + (h >> 2) * 128,
;                                           QQ + q0 * LDQQ + h * 128, (char*)lds, (LAS unsigned char*)lds);
.LBB0_99:
	s_mul_hi_i32 s2, s12, 0x2aaaaaab
	s_lshr_b32 s3, s2, 31
	s_lshr_b32 s2, s2, 8
	s_add_i32 s2, s2, s3
	s_mulk_i32 s2, 0x600
	s_sub_i32 s13, s12, s2
	s_ashr_i32 s8, s13, 8
	s_ashr_i32 s9, s8, 31
	s_lshl_b32 s4, s13, 5
	s_lshl_b64 s[2:3], s[8:9], 13
	s_and_b32 s4, s4, 0x1f00
	s_or_b32 s2, s2, s4
	s_mulk_i32 s3, 0x1800
	s_mul_hi_u32 s5, s2, 0x1800
	s_and_b32 s16, s13, 7
	s_add_i32 s4, s12, 0x5ff
	s_add_i32 s5, s5, s3
	s_mulk_i32 s2, 0x1800
	s_add_u32 s17, s92, s2
	s_addc_u32 s18, s93, s5
	s_cmpk_gt_u32 s4, 0xbfe
	s_mov_b64 s[2:3], -1
	s_cbranch_scc0 .LBB0_115
	s_lshl_b32 s2, s16, 7
	s_lshl_b32 s3, s16, 8
	s_add_u32 s4, s17, s3
	s_addc_u32 s5, s18, 0
	s_add_u32 s2, s17, s2
	s_addc_u32 s3, s18, 0
	s_add_u32 s6, s2, 0x1000
	s_addc_u32 s7, s3, 0
	s_lshl_b64 s[2:3], s[8:9], 25
	s_add_u32 s10, s82, s2
	s_addc_u32 s11, s83, s3
	s_lshl_b32 s30, s16, 9
	s_add_u32 s24, s10, s30
	s_addc_u32 s25, s11, 0
	s_lshl_b64 s[10:11], s[8:9], 24
	v_readlane_b32 s14, v248, 43
	s_waitcnt vmcnt(0)
	v_mov_b32_e32 v64, v184
	v_readlane_b32 s15, v248, 44
	s_add_u32 s36, s14, s10
	s_addc_u32 s37, s15, s11
	v_readfirstlane_b32 s9, v64
	s_ashr_i32 s27, s9, 6
	v_and_b32_e32 v98, 63, v64
	s_lshl_b32 s14, s27, 3
	v_lshlrev_b32_e32 v82, 3, v98
	v_lshrrev_b32_e32 v66, 1, v64
	v_bfe_u32 v65, v64, 4, 2
	v_and_b32_e32 v2, 15, v64
	v_bfe_u32 v99, v64, 2, 2
	s_and_b32 s31, s14, 0xffff0
	v_and_b32_e32 v100, 8, v66
	s_lshl_b32 s15, s27, 2
	v_and_b32_e32 v83, 24, v82
	v_bfe_u32 v103, v64, 3, 3
	s_and_b32 s34, s15, 4
	v_or3_b32 v0, v100, v99, s31
	v_and_or_b32 v3, v64, 32, v83
	v_bitop3_b32 v2, v65, v2, 4 bitop3:0x36
	v_or_b32_e32 v9, s14, v103
	v_or_b32_e32 v0, s34, v0
	v_lshlrev_b32_e32 v3, 1, v3
	v_lshlrev_b32_e32 v102, 4, v2
	s_and_b32 s32, s27, 1
	s_lshl_b32 s32, s32, 7
	v_xor_b32_e32 v102, s32, v102
	v_lshrrev_b32_e32 v2, 1, v9
	v_bitop3_b32 v5, v65, v64, 15 bitop3:0x78
	v_lshl_or_b32 v0, v0, 12, v3
	v_or_b32_e32 v3, 4, v65
	v_xor_b32_e32 v2, v2, v64
	s_lshl_b32 s15, s27, 11
	v_or_b32_e32 v4, s14, v65
	v_lshlrev_b32_e32 v101, 4, v5
	v_xor_b32_e32 v101, s32, v101
	v_or_b32_e32 v3, s14, v3
	v_lshlrev_b32_e32 v2, 4, v2
	s_add_i32 s19, s15, 0
	v_lshl_or_b32 v6, v4, 12, v101
	v_lshl_or_b32 v7, v3, 12, v102
	v_and_b32_e32 v104, 0x70, v2
	s_add_i32 m0, s19, 0xc000
	v_lshl_add_u64 v[2:3], s[24:25], 0, v[0:1]
	s_mov_b64 s[38:39], 0x100
	global_load_lds_dwordx4 v6, s[24:25]
	v_lshl_add_u64 v[4:5], v[2:3], 0, s[38:39]
	s_mov_b32 m0, s19
	s_and_b32 s9, s9, 0x3fffffc0
	global_load_lds_dwordx4 v[4:5], off
	s_add_i32 m0, s19, 0xc400
	s_mov_b64 s[38:39], 0x180
	s_lshl_b32 s9, s9, 2
	global_load_lds_dwordx4 v7, s[24:25]
	v_lshl_add_u64 v[2:3], v[2:3], 0, s[38:39]
	s_add_i32 m0, s19, 0x400
	s_add_i32 s9, s9, 0
	global_load_lds_dwordx4 v[2:3], off
	v_lshl_or_b32 v2, v9, 11, v104
	v_mov_b32_e32 v3, v1
	s_lshl_b32 s14, s27, 10
	s_add_i32 s26, 0, 0x18000
	s_add_i32 s9, s9, 0x1e000
	v_lshl_add_u64 v[2:3], s[36:37], 0, v[2:3]
	s_mov_b64 s[36:37], 0x600
	s_add_i32 s23, s26, s14
	v_lshl_add_u64 v[4:5], v[2:3], 0, s[36:37]
	s_add_u32 s36, s24, 0x40000
	s_addc_u32 s37, s25, 0
	s_mov_b32 m0, s23
	s_add_u32 s24, s24, 0x40100
	global_load_lds_dwordx4 v[4:5], off
	s_addc_u32 s25, s25, 0
	s_add_i32 m0, s19, 0x10000
	v_or_b32_e32 v8, 0x80, v0
	global_load_lds_dwordx4 v6, s[36:37]
	s_add_i32 m0, s19, 0x4000
	s_add_i32 s14, s14, 0
	global_load_lds_dwordx4 v0, s[24:25]
	s_add_i32 m0, s19, 0x10400
	v_and_b32_e32 v193, 31, v64
	global_load_lds_dwordx4 v7, s[36:37]
	s_add_i32 m0, s19, 0x4400
	v_bfe_u32 v194, v64, 5, 1
	global_load_lds_dwordx4 v8, s[24:25]
	s_mov_b64 s[24:25], 0x20600
	v_lshl_add_u64 v[2:3], v[2:3], 0, s[24:25]
	s_add_i32 m0, s14, 0x1a000
	s_lshl_b32 s14, s27, 5
	global_load_lds_dwordx4 v[2:3], off
	v_or_b32_e32 v0, s14, v193
	v_mov_b64_e32 v[2:3], s[6:7]
	v_lshlrev_b32_e32 v166, 4, v194
	v_mov_b32_e32 v167, v1
	v_mad_i64_i32 v[2:3], s[6:7], v0, s33, v[2:3]
	v_mov_b32_e32 v16, v1
	v_mov_b32_e32 v17, v1
	v_mov_b32_e32 v18, v1
	v_mov_b32_e32 v19, v1
	v_mov_b32_e32 v20, v1
	v_mov_b32_e32 v21, v1
	v_mov_b32_e32 v22, v1
	v_mov_b32_e32 v23, v1
	v_mov_b32_e32 v24, v1
	v_mov_b32_e32 v25, v1
	v_mov_b32_e32 v26, v1
	v_mov_b32_e32 v27, v1
	v_mov_b32_e32 v28, v1
	v_mov_b32_e32 v29, v1
	v_mov_b32_e32 v30, v1
	v_mov_b32_e32 v31, v1
	v_lshl_add_u64 v[14:15], v[2:3], 0, v[166:167]
	global_load_dwordx4 v[2:5], v[14:15], off
	global_load_dwordx4 v[6:9], v[14:15], off offset:32
	global_load_dwordx4 v[10:13], v[14:15], off offset:64
	global_load_dwordx4 v[32:35], v[14:15], off offset:96
	v_mov_b64_e32 v[14:15], s[4:5]
	v_mad_i64_i32 v[14:15], s[6:7], v0, s33, v[14:15]
	v_lshl_add_u64 v[14:15], v[14:15], 0, v[166:167]
	global_load_dwordx4 v[158:161], v[14:15], off offset:2048
	global_load_dwordx4 v[154:157], v[14:15], off offset:2080
	global_load_dwordx4 v[150:153], v[14:15], off offset:2112
	global_load_dwordx4 v[146:149], v[14:15], off offset:2144
	global_load_dwordx4 v[142:145], v[14:15], off offset:2176
	global_load_dwordx4 v[138:141], v[14:15], off offset:2208
	global_load_dwordx4 v[134:137], v[14:15], off offset:2240
	global_load_dwordx4 v[130:133], v[14:15], off offset:2272
	s_lshl_b32 s6, s27, 12
	s_add_i32 s6, s6, 0
	v_lshlrev_b32_e32 v84, 4, v98
	s_add_i32 s6, s6, 0x1e800
	v_add_u32_e32 v198, s6, v84
	s_waitcnt vmcnt(0)
	ds_write_b128 v198, v[2:5]
	ds_write_b128 v198, v[6:9] offset:1024
	ds_write_b128 v198, v[10:13] offset:2048
	ds_write_b128 v198, v[32:35] offset:3072
	v_lshlrev_b32_e32 v2, 4, v64
	v_lshlrev_b32_e32 v0, 8, v193
	v_and_b32_e32 v10, 0xf0, v2
	v_bitop3_b32 v210, v166, v0, v10 bitop3:0xde
	v_add_u32_e32 v6, 0, v210
	s_waitcnt vmcnt(0)
	s_waitcnt lgkmcnt(0)
	s_barrier
; template <bool MLA>
; __device__ __forceinline__ void qkt(f32x16& p0, f32x16& p1, const char* Ks, const char* KRs, const bf16x8* qr, const char* qrl, const f32x16& negm, int r32, int hi) {
; #pragma unroll
;   for (int d0 = 0; d0 < 8; ++d0) { int cb = (d0 * 16 + hi * 8) * 2;
;     bf16x8 b0 = *reinterpret_cast<const bf16x8*>(Ks + KSWZ(r32, cb));
;     bf16x8 b1 = *reinterpret_cast<const bf16x8*>(Ks + KSWZ(32 + r32, cb));
;     if (d0 == 0) { p0 = __builtin_amdgcn_mfma_f32_32x32x16_bf16(b0, qr[0], negm, 0, 0, 0); p1 = __builtin_amdgcn_mfma_f32_32x32x16_bf16(b1, qr[0], negm, 0, 0, 0); }
;     else { p0 = __builtin_amdgcn_mfma_f32_32x32x16_bf16(b0, qr[d0], p0, 0, 0, 0); p1 = __builtin_amdgcn_mfma_f32_32x32x16_bf16(b1, qr[d0], p1, 0, 0, 0); } }
;   if constexpr (MLA) {
; #pragma unroll
;     for (int d0 = 0; d0 < 4; ++d0) { int ch = d0 * 2 + hi;
;       bf16x8 b0 = *reinterpret_cast<const bf16x8*>(KRs + KRSWZ(r32, ch));
;       bf16x8 b1 = *reinterpret_cast<const bf16x8*>(KRs + KRSWZ(32 + r32, ch));
;       const bf16x8 qq = *reinterpret_cast<const bf16x8*>(qrl + d0 * 1024);
;       p0 = __builtin_amdgcn_mfma_f32_32x32x16_bf16(b0, qq, p0, 0, 0, 0);
;       p1 = __builtin_amdgcn_mfma_f32_32x32x16_bf16(b1, qq, p1, 0, 0, 0); }
;   }
; }
; template <bool MLA> ...
;     ...
;   qkt<MLA>(pA0, pA1, K_lds, KR_lds, qr, qrl, negm, r32, hi); partialSM<true, false>(pA0, pA1, negm, m_reg, alA);
;   int s_prev = 0, s_cur = 1, s_next = 2;
	ds_read_b128 v[2:5], v6 offset:49152
	ds_read_b128 v[6:9], v6 offset:57344
	s_waitcnt lgkmcnt(1)
	v_mfma_f32_32x32x16_bf16 v[48:63], v[2:5], v[158:161], v[16:31]
	v_or_b32_e32 v2, 32, v166
	v_bitop3_b32 v209, v2, v0, v10 bitop3:0xde
	v_lshlrev_b32_e32 v14, 7, v193
	v_bfe_u32 v15, v64, 1, 3
	v_lshlrev_b32_e32 v105, 1, v64
	s_movk_i32 s6, 0xc0
	s_cmp_lg_u32 0, -1
	s_waitcnt lgkmcnt(0)
	v_mfma_f32_32x32x16_bf16 v[32:47], v[6:9], v[158:161], v[16:31]
	v_add_u32_e32 v6, 0, v209
	ds_read_b128 v[2:5], v6 offset:49152
	ds_read_b128 v[6:9], v6 offset:57344
	s_mov_b32 s25, 2
	s_mov_b32 s24, 1
	s_mov_b32 s35, 0
	v_lshl_add_u32 v167, v193, 2, s9
	v_mov_b32_e32 v195, 0
	s_waitcnt lgkmcnt(1)
	v_mfma_f32_32x32x16_bf16 v[48:63], v[2:5], v[154:157], v[48:63]
	v_or_b32_e32 v2, 64, v166
	v_bitop3_b32 v208, v2, v0, v10 bitop3:0xde
	v_mov_b32_e32 v211, 1.0
	s_waitcnt lgkmcnt(0)
	v_mfma_f32_32x32x16_bf16 v[32:47], v[6:9], v[154:157], v[32:47]
	v_add_u32_e32 v6, 0, v208
	ds_read_b128 v[2:5], v6 offset:49152
	ds_read_b128 v[6:9], v6 offset:57344
	s_waitcnt lgkmcnt(1)
	v_mfma_f32_32x32x16_bf16 v[48:63], v[2:5], v[150:153], v[48:63]
	v_or_b32_e32 v2, 0x60, v166
	v_bitop3_b32 v207, v2, v0, v10 bitop3:0xde
	s_waitcnt lgkmcnt(0)
	v_mfma_f32_32x32x16_bf16 v[32:47], v[6:9], v[150:153], v[32:47]
	v_add_u32_e32 v6, 0, v207
	ds_read_b128 v[2:5], v6 offset:49152
	ds_read_b128 v[6:9], v6 offset:57344
	s_waitcnt lgkmcnt(1)
	v_mfma_f32_32x32x16_bf16 v[48:63], v[2:5], v[146:149], v[48:63]
	v_or_b32_e32 v2, 0x80, v166
	v_bitop3_b32 v206, v2, v0, v10 bitop3:0xde
	s_waitcnt lgkmcnt(0)
	v_mfma_f32_32x32x16_bf16 v[32:47], v[6:9], v[146:149], v[32:47]
	v_add_u32_e32 v6, 0, v206
	ds_read_b128 v[2:5], v6 offset:49152
	ds_read_b128 v[6:9], v6 offset:57344
	s_waitcnt lgkmcnt(1)
	v_mfma_f32_32x32x16_bf16 v[48:63], v[2:5], v[142:145], v[48:63]
	v_or_b32_e32 v2, 0xa0, v166
	v_bitop3_b32 v205, v2, v0, v10 bitop3:0xde
	s_waitcnt lgkmcnt(0)
	v_mfma_f32_32x32x16_bf16 v[32:47], v[6:9], v[142:145], v[32:47]
	v_add_u32_e32 v6, 0, v205
	ds_read_b128 v[2:5], v6 offset:49152
	ds_read_b128 v[6:9], v6 offset:57344
	s_waitcnt lgkmcnt(1)
	v_mfma_f32_32x32x16_bf16 v[48:63], v[2:5], v[138:141], v[48:63]
	v_or_b32_e32 v2, 0xc0, v166
	v_bitop3_b32 v204, v2, v0, v10 bitop3:0xde
	s_waitcnt lgkmcnt(0)
	v_mfma_f32_32x32x16_bf16 v[32:47], v[6:9], v[138:141], v[32:47]
	v_add_u32_e32 v6, 0, v204
	ds_read_b128 v[2:5], v6 offset:49152
	ds_read_b128 v[6:9], v6 offset:57344
	s_waitcnt lgkmcnt(1)
	v_mfma_f32_32x32x16_bf16 v[48:63], v[2:5], v[134:137], v[48:63]
	v_or_b32_e32 v2, 0xe0, v166
	v_bitop3_b32 v203, v2, v0, v10 bitop3:0xde
	v_add_u32_e32 v0, 0, v203
	s_waitcnt lgkmcnt(0)
	v_mfma_f32_32x32x16_bf16 v[32:47], v[6:9], v[134:137], v[32:47]
	ds_read_b128 v[2:5], v0 offset:49152
	ds_read_b128 v[6:9], v0 offset:57344
	v_bitop3_b32 v0, v194, v66, 7 bitop3:0x78
	v_lshl_or_b32 v200, v0, 4, v14
	v_add_u32_e32 v0, s26, v200
	s_waitcnt lgkmcnt(1)
	v_mfma_f32_32x32x16_bf16 v[48:63], v[2:5], v[130:133], v[48:63]
	s_waitcnt lgkmcnt(0)
	v_mfma_f32_32x32x16_bf16 v[32:47], v[6:9], v[130:133], v[32:47]
	ds_read_b128 v[2:5], v0
	ds_read_b128 v[6:9], v198
	ds_read_b128 v[10:13], v0 offset:4096
	ds_read_b128 v[66:69], v198 offset:1024
	v_bitop3_b32 v0, v194, v15, 2 bitop3:0x36
	v_lshl_or_b32 v201, v0, 4, v14
	v_mov_b32_e32 v0, v1
	s_waitcnt lgkmcnt(2)
	v_mfma_f32_32x32x16_bf16 v[48:63], v[2:5], v[6:9], v[48:63]
	s_waitcnt lgkmcnt(1)
	v_mfma_f32_32x32x16_bf16 v[32:47], v[10:13], v[6:9], v[32:47]
	v_add_u32_e32 v6, s26, v201
	ds_read_b128 v[2:5], v6
	ds_read_b128 v[6:9], v6 offset:4096
	s_waitcnt lgkmcnt(1)
	v_mfma_f32_32x32x16_bf16 v[48:63], v[2:5], v[66:69], v[48:63]
	v_bitop3_b32 v5, v194, v15, 4 bitop3:0x36
	v_lshl_or_b32 v199, v5, 4, v14
	v_add_u32_e32 v70, s26, v199
	ds_read_b128 v[10:13], v70
	v_mov_b32_e32 v2, v1
	v_mov_b32_e32 v3, v1
	v_mov_b32_e32 v4, v1
	s_waitcnt lgkmcnt(1)
	v_mfma_f32_32x32x16_bf16 v[32:47], v[6:9], v[66:69], v[32:47]
	ds_read_b128 v[66:69], v198 offset:2048
	ds_read_b128 v[70:73], v70 offset:4096
	ds_read_b128 v[74:77], v198 offset:3072
	v_mov_b32_e32 v5, v1
	v_mov_b32_e32 v6, v1
	v_mov_b32_e32 v7, v1
	v_mov_b32_e32 v8, v1
	v_mov_b32_e32 v9, v1
	s_waitcnt lgkmcnt(2)
	v_mfma_f32_32x32x16_bf16 v[48:63], v[10:13], v[66:69], v[48:63]
	v_bitop3_b32 v12, v194, v15, 6 bitop3:0x36
	v_lshl_or_b32 v202, v12, 4, v14
	v_add_u32_e32 v85, s26, v202
	ds_read_b128 v[78:81], v85
	v_mov_b32_e32 v14, v1
	v_mov_b32_e32 v15, v1
	v_mov_b32_e32 v10, v1
	s_waitcnt lgkmcnt(2)
	v_mfma_f32_32x32x16_bf16 v[32:47], v[70:73], v[66:69], v[32:47]
	ds_read_b128 v[66:69], v85 offset:4096
	v_and_b32_e32 v70, 32, v105
	v_and_or_b32 v70, v84, s6, v70
	v_and_b32_e32 v71, 0x100, v82
	v_or3_b32 v196, v70, v71, v83
	s_cselect_b32 s6, 0, 0
	s_lshl_b32 s36, s27, 14
	s_waitcnt lgkmcnt(1)
; __device__ __forceinline__ float max3f(float a, float b, float c) { return __builtin_fmaxf(__builtin_fmaxf(a, b), c); }
; template <bool FIRST, bool MLA>
; __device__ __forceinline__ void partialSM(f32x16& p0, f32x16& p1, f32x16& negm, float& m_reg, float& alpha) {
;   float a = max3f(p0[0], p0[1], p1[0]), b = max3f(p0[2], p0[3], p1[1]); a = max3f(a, p1[2], p1[3]);
; #pragma unroll
;   for (int r = 4; r < 16; r += 4) { a = max3f(a, p0[r], p0[r + 1]); b = max3f(b, p0[r + 2], p0[r + 3]); a = max3f(a, p1[r], p1[r + 1]); b = max3f(b, p1[r + 2], p1[r + 3]); }
;   float pmax = fmaxf(a, b);
;   { auto rr = __builtin_amdgcn_permlane32_swap(__float_as_uint(pmax), __float_as_uint(pmax), false, false);
;     pmax = fmaxf(__uint_as_float(rr[0]), __uint_as_float(rr[1])); }
;   alpha = 1.f;
;   if constexpr (MLA) {
;     if (FIRST) m_reg = pmax;
;     else if (!__builtin_expect(__all(pmax - m_reg <= THR2), 1)) { const float mn = fmaxf(m_reg, pmax); alpha = __builtin_amdgcn_exp2f(m_reg - mn); m_reg = mn; }
; #pragma unroll
;     for (int r = 0; r < 16; ++r) { p0[r] -= m_reg; p1[r] -= m_reg; }
;   } else
;   if (FIRST || __builtin_expect(__any(pmax > THR2), 0)) {
;     const float d = FIRST ? pmax : fmaxf(pmax, 0.f);
; #pragma unroll
;     for (int r = 0; r < 16; ++r) { p0[r] -= d; p1[r] -= d; }
; #pragma unroll
;     for (int r = 0; r < 16; ++r) negm[r] -= d;
;     asm volatile("" : "+v"(negm));
;     if (!FIRST) alpha = __builtin_amdgcn_exp2f(-d);
;   }
; #pragma unroll
;   for (int r = 0; r < 16; ++r) p0[r] = __builtin_amdgcn_exp2f(p0[r]);
; }
; template <bool MLA> ...
;     ...
;   DMA_TILE(0, 0); DMA_TILE(1, 1);
;   float l_reg = 0, m_reg = 0; f32x16 o[4] = {}; bf16x8 qr[8]; f32x16 negm = {}; asm volatile("" : "+v"(negm));
	v_mfma_f32_32x32x16_bf16 v[48:63], v[78:81], v[74:77], v[48:63]
	v_mov_b32_e32 v11, v1
	v_mov_b32_e32 v12, v1
	v_mov_b32_e32 v13, v1
	s_mov_b32 s26, -1
	v_add_u32_e32 v197, s6, v196
	v_cmp_gt_u32_e64 s[6:7], 32, v98
	s_waitcnt lgkmcnt(0)
	v_mfma_f32_32x32x16_bf16 v[32:47], v[66:69], v[74:77], v[32:47]
	s_nop 3
	v_max_f32_e32 v66, v49, v49
	v_max_f32_e32 v67, v48, v48
	v_max_f32_e32 v66, v67, v66
	s_nop 4
	v_max3_f32 v67, v50, v51, v33
	v_max3_f32 v66, v66, v32, v34
	v_max3_f32 v66, v66, v35, v52
	v_max3_f32 v67, v67, v54, v55
	v_max3_f32 v66, v66, v53, v36
	v_max3_f32 v67, v67, v38, v39
	v_max3_f32 v66, v66, v37, v56
	v_max3_f32 v67, v67, v58, v59
	v_max3_f32 v66, v66, v57, v40
	v_max3_f32 v67, v67, v42, v43
	v_max3_f32 v66, v66, v41, v60
	v_max3_f32 v67, v67, v62, v63
	v_max3_f32 v66, v66, v61, v44
	v_max3_f32 v67, v67, v46, v47
	v_max3_f32 v66, v66, v45, v67
	v_mov_b32_e32 v67, v66
	s_nop 1
	v_permlane32_swap_b32_e32 v66, v67
	v_max_f32_e32 v67, v67, v67
	v_max_f32_e32 v66, v66, v66
	v_max_f32_e32 v66, v66, v67
	v_sub_f32_e32 v48, v48, v66
	v_sub_f32_e32 v49, v49, v66
	v_sub_f32_e32 v50, v50, v66
	v_sub_f32_e32 v51, v51, v66
	v_sub_f32_e32 v52, v52, v66
	v_sub_f32_e32 v53, v53, v66
	v_sub_f32_e32 v54, v54, v66
	v_sub_f32_e32 v55, v55, v66
	v_sub_f32_e32 v56, v56, v66
	v_sub_f32_e32 v57, v57, v66
	v_sub_f32_e32 v58, v58, v66
	v_sub_f32_e32 v59, v59, v66
	v_sub_f32_e32 v60, v60, v66
	v_sub_f32_e32 v61, v61, v66
	v_sub_f32_e32 v62, v62, v66
	v_sub_f32_e32 v63, v63, v66
	v_sub_f32_e32 v97, v47, v66
	v_sub_f32_e32 v96, v46, v66
	v_sub_f32_e32 v95, v45, v66
	v_sub_f32_e32 v94, v44, v66
	v_sub_f32_e32 v93, v43, v66
	v_sub_f32_e32 v92, v42, v66
	v_sub_f32_e32 v91, v41, v66
	v_sub_f32_e32 v90, v40, v66
	v_sub_f32_e32 v89, v39, v66
	v_sub_f32_e32 v88, v38, v66
	v_sub_f32_e32 v87, v37, v66
	v_sub_f32_e32 v86, v36, v66
	v_sub_f32_e32 v85, v35, v66
	v_sub_f32_e32 v84, v34, v66
	v_sub_f32_e32 v83, v33, v66
	v_sub_f32_e32 v82, v32, v66
	v_sub_f32_e32 v81, v31, v66
	v_sub_f32_e32 v80, v30, v66
	v_sub_f32_e32 v79, v29, v66
	v_sub_f32_e32 v78, v28, v66
	v_sub_f32_e32 v77, v27, v66
	v_sub_f32_e32 v76, v26, v66
	v_sub_f32_e32 v75, v25, v66
	v_sub_f32_e32 v74, v24, v66
	v_sub_f32_e32 v73, v23, v66
	v_sub_f32_e32 v72, v22, v66
	v_sub_f32_e32 v71, v21, v66
	v_sub_f32_e32 v70, v20, v66
	v_sub_f32_e32 v69, v19, v66
	v_sub_f32_e32 v68, v18, v66
	v_sub_f32_e32 v67, v17, v66
	v_sub_f32_e32 v66, v16, v66
	v_lshlrev_b32_e32 v16, 11, v103
	v_or3_b32 v16, s36, v16, v104
	s_load_dwordx4 s[36:39], s[0:1], 0x120
	v_mov_b32_e32 v17, v1
	v_and_b32_e32 v18, 3, v64
	v_lshlrev_b32_e32 v18, 4, v18
	v_exp_f32_e32 v227, v48
	s_waitcnt lgkmcnt(0)
	s_add_u32 s10, s38, s10
	s_addc_u32 s11, s39, s11
	v_lshl_add_u64 v[168:169], s[10:11], 0, v[16:17]
	s_or_b32 s2, s2, s30
	v_or_b32_e32 v16, s31, v100
	v_or3_b32 v16, v16, s34, v99
	s_add_u32 s2, s38, s2
	v_lshlrev_b32_e32 v16, 12, v16
	v_and_b32_e32 v17, 64, v105
	s_addc_u32 s3, s39, s3
	s_lshl_b32 s10, s27, 15
	v_or3_b32 v16, v16, v17, v18
	v_mov_b32_e32 v17, v1
	v_lshl_or_b32 v18, v65, 12, s10
	v_exp_f32_e32 v229, v49
	v_exp_f32_e32 v225, v50
	v_exp_f32_e32 v228, v51
	v_exp_f32_e32 v224, v52
	v_exp_f32_e32 v226, v53
	v_exp_f32_e32 v222, v54
	v_exp_f32_e32 v223, v55
	v_exp_f32_e32 v219, v56
	v_exp_f32_e32 v221, v57
	v_exp_f32_e32 v218, v58
	v_exp_f32_e32 v220, v59
	v_exp_f32_e32 v215, v60
	v_exp_f32_e32 v217, v61
	v_exp_f32_e32 v214, v62
	v_exp_f32_e32 v216, v63
	v_lshl_add_u64 v[170:171], s[2:3], 0, v[16:17]
	v_or_b32_e32 v16, v18, v101
	s_movk_i32 s10, 0x4000
	v_lshl_add_u64 v[172:173], s[2:3], 0, v[16:17]
	v_or3_b32 v16, v18, v102, s10
	v_mov_b64_e32 v[64:65], v[14:15]
	v_mov_b64_e32 v[48:49], v[14:15]
	v_mov_b64_e32 v[32:33], v[14:15]
	v_lshl_add_u64 v[174:175], s[2:3], 0, v[16:17]
	v_mov_b64_e32 v[62:63], v[12:13]
	v_mov_b64_e32 v[60:61], v[10:11]
	v_mov_b64_e32 v[58:59], v[8:9]
	v_mov_b64_e32 v[56:57], v[6:7]
	v_mov_b64_e32 v[54:55], v[4:5]
	v_mov_b64_e32 v[52:53], v[2:3]
	v_mov_b64_e32 v[50:51], v[0:1]
	v_mov_b64_e32 v[46:47], v[12:13]
	v_mov_b64_e32 v[44:45], v[10:11]
	v_mov_b64_e32 v[42:43], v[8:9]
	v_mov_b64_e32 v[40:41], v[6:7]
	v_mov_b64_e32 v[38:39], v[4:5]
	v_mov_b64_e32 v[36:37], v[2:3]
	v_mov_b64_e32 v[34:35], v[0:1]
	v_mov_b64_e32 v[30:31], v[12:13]
	v_mov_b64_e32 v[28:29], v[10:11]
	v_mov_b64_e32 v[26:27], v[8:9]
	v_mov_b64_e32 v[24:25], v[6:7]
	v_mov_b64_e32 v[22:23], v[4:5]
	v_mov_b64_e32 v[20:21], v[2:3]
	v_mov_b64_e32 v[18:19], v[0:1]
	v_mov_b64_e32 v[16:17], v[14:15]
	v_mov_b64_e32 v[14:15], v[12:13]
	v_mov_b64_e32 v[12:13], v[10:11]
	v_mov_b64_e32 v[10:11], v[8:9]
	v_mov_b64_e32 v[8:9], v[6:7]
	v_mov_b64_e32 v[6:7], v[4:5]
	v_mov_b64_e32 v[4:5], v[2:3]
	v_mov_b64_e32 v[2:3], v[0:1]

; #define LAS __attribute__((address_space(3)))
; __device__ __forceinline__ int opaque_tid() { int t = threadIdx.x; asm volatile("" : "+v"(t)); return t; }
; template <bool MLA> ...
;     ...
;   const int tid = opaque_tid(), wid = __builtin_amdgcn_readfirstlane(tid >> 6), lane = tid & 63, r32 = lane & 31, hi = lane >> 5;
;   char* V_lds = lds + OFF_V; char* K_lds = lds + OFF_K; char* KR_lds = lds + OFF_KR;
;   float* ws = (float*)(lds + OFF_WS) + wid * 64; float* li_l = ws; float* al_l = ws + 32;
;   unsigned koff[2], voff[2], kroff = 0;
; #pragma unroll
;   for (int i = 0; i < 2; ++i) { const int p = 2 * wid + i;
;     { const int row = 4 * p + (lane >> 4), pc = lane & 15, c = pc ^ (row & 7); koff[i] = (unsigned)(row * LDK + c * 8) * 2u; }
;     { const int o = p * 1024 + lane * 16, sub = o >> 9, w_ = (o & 511) >> 1, kk = (sub >> 2) * 8 + (w_ >> 5), k = (kk & ~0xC) | ((kk & 4) << 1) | ((kk & 8) >> 1), c = (sub & 3) * 32 + (w_ & 31);
;       voff[i] = (unsigned)(k * LDK + c) * 2u; } }
;   if constexpr (MLA) { const int row = 8 * wid + (lane >> 3), pc = lane & 7, ch = pc ^ ((row >> 1) & 7); kroff = (unsigned)(row * LDKR + ch * 8) * 2u; }
;     ...
;   DMA_TILE(0, 0); DMA_TILE(1, 1);
;   float l_reg = 0, m_reg = 0; f32x16 o[4] = {}; bf16x8 qr[8]; f32x16 negm = {}; asm volatile("" : "+v"(negm));
;   char* qrl = lds + OFF_QR + wid * 4096 + lane * 16;
;   { const bf16_t* Qw = Qb + (long)(wid * QBLK + r32) * LDQ + hi * 8;
; #pragma unroll
;     for (int d0 = 0; d0 < 8; ++d0) qr[d0] = *reinterpret_cast<const bf16x8*>(Qw + d0 * 16);
;     if constexpr (MLA) { const bf16_t* Qw2 = Qrb + (long)(wid * QBLK + r32) * LDQ + hi * 8;
; #pragma unroll
;       for (int d0 = 0; d0 < 4; ++d0) *reinterpret_cast<bf16x8*>(qrl + d0 * 1024) = *reinterpret_cast<const bf16x8*>(Qw2 + d0 * 16); } }
;   const int vb0 = (int)(uintptr_t)V_lds + v_rd_base(lane);
;     ...
;   f32x16 pA0, pA1, pB0, pB1; float alA, alB; bf16x8 pa0, pa1, pa2, pa3;
;   WAIT_BAR();
;   qkt<MLA>(pA0, pA1, K_lds, KR_lds, qr, qrl, negm, r32, hi); partialSM<true, false>(pA0, pA1, negm, m_reg, alA);
; __global__ void __launch_bounds__(512) mega_fwd(Params p) {
;     ...
;                     att::attn_unit<false>(QQ + q0 * LDQQ + h * 128, nullptr, QQ + row0 * LDQQ + 2560 + (h >> 2) * 128, nullptr, QQ + row0 * LDQQ + 2816 + (h >> 2) * 128,
;                                           QQ + q0 * LDQQ + h * 128, (char*)lds, (LAS unsigned char*)lds);
.LBB0_124:
	s_lshl_b32 s2, s16, 8
	s_add_u32 s4, s17, s2
	s_addc_u32 s5, s18, 0
	s_mul_i32 s2, s8, 0x3000000
	s_mul_hi_i32 s3, s8, 0x3000000
	s_add_u32 s6, s92, s2
	s_addc_u32 s7, s93, s3
	s_lshl_b32 s8, s16, 6
	s_and_b32 s8, s8, 0x100
	s_add_u32 s6, s6, s8
	s_addc_u32 s7, s7, 0
	v_mov_b32_e32 v74, v184
	s_add_u32 s16, s6, 0x1400
	s_addc_u32 s17, s7, 0
	v_readfirstlane_b32 s9, v74
	s_ashr_i32 s8, s9, 6
	s_and_b32 s9, s9, 0x3fffffc0
	s_lshl_b32 s9, s9, 2
	s_lshl_b32 s11, s8, 3
	v_lshrrev_b32_e32 v0, 1, v74
	s_add_i32 s10, s9, 0
	v_bfe_u32 v99, v74, 4, 2
	v_bfe_u32 v100, v74, 2, 2
	s_and_b32 s9, s11, 0x7ffffff0
	v_and_b32_e32 v101, 8, v0
	s_lshl_b32 s14, s8, 2
	v_and_b32_e32 v98, 63, v74
	s_and_b32 s19, s14, 4
	v_or3_b32 v0, v101, v100, s9
	s_waitcnt vmcnt(0)
	v_or_b32_e32 v3, s11, v99
	v_bitop3_b32 v4, v99, v74, 15 bitop3:0x78
	v_lshlrev_b32_e32 v75, 3, v98
	v_or_b32_e32 v0, s19, v0
	s_movk_i32 s26, 0xc00
	v_lshlrev_b32_e32 v104, 4, v4
	s_and_b32 s32, s8, 1
	s_lshl_b32 s32, s32, 7
	v_xor_b32_e32 v104, s32, v104
	v_mul_lo_u32 v3, v3, s33
	v_and_b32_e32 v2, 15, v74
	v_and_b32_e32 v102, 32, v74
	v_and_b32_e32 v103, 24, v75
	v_mul_lo_u32 v0, v0, s26
	v_or_b32_e32 v6, v3, v104
	v_or_b32_e32 v3, 4, v99
	v_or3_b32 v0, v0, v102, v103
	v_or_b32_e32 v3, s11, v3
	v_bitop3_b32 v2, v99, v2, 4 bitop3:0x36
	s_lshl_b32 s14, s8, 11
	v_lshlrev_b32_e32 v0, 1, v0
	v_lshlrev_b32_e32 v105, 4, v2
	v_xor_b32_e32 v105, s32, v105
	v_mul_lo_u32 v2, v3, s33
	s_add_i32 s15, s14, 0
	v_or_b32_e32 v7, v105, v2
	s_add_i32 m0, s15, 0xc000
	v_lshl_add_u64 v[2:3], s[6:7], 0, v[0:1]
	s_mov_b64 s[24:25], 0x1600
	global_load_lds_dwordx4 v6, s[16:17]
	v_lshl_add_u64 v[4:5], v[2:3], 0, s[24:25]
	s_mov_b32 m0, s15
	s_add_i32 s10, s10, 0x1e000
	global_load_lds_dwordx4 v[4:5], off
	s_add_i32 m0, s15, 0xc400
	v_or_b32_e32 v8, 0x80, v0
	global_load_lds_dwordx4 v7, s[16:17]
	s_mov_b64 s[16:17], 0x1680
	s_add_i32 m0, s15, 0x400
	v_lshl_add_u64 v[2:3], v[2:3], 0, s[16:17]
	s_add_u32 s16, s6, 0x61400
	s_addc_u32 s17, s7, 0
	s_add_u32 s6, s6, 0x61600
	global_load_lds_dwordx4 v[2:3], off
	s_addc_u32 s7, s7, 0
	s_add_i32 m0, s15, 0x10000
	v_mov_b32_e32 v14, v1
	global_load_lds_dwordx4 v6, s[16:17]
	s_add_i32 m0, s15, 0x4000
	v_mov_b32_e32 v15, v1
	global_load_lds_dwordx4 v0, s[6:7]
	s_add_i32 m0, s15, 0x10400
	v_and_b32_e32 v178, 31, v74
	global_load_lds_dwordx4 v7, s[16:17]
	s_add_i32 m0, s15, 0x4400
	v_mov_b32_e32 v0, v1
	global_load_lds_dwordx4 v8, s[6:7]
	v_mov_b32_e32 v2, v1
	v_mov_b32_e32 v3, v1
	v_mov_b32_e32 v4, v1
	v_mov_b32_e32 v5, v1
	v_mov_b32_e32 v6, v1
	v_mov_b32_e32 v7, v1
	v_mov_b32_e32 v8, v1
	v_mov_b32_e32 v9, v1
	v_mov_b32_e32 v10, v1
	v_mov_b32_e32 v11, v1
	v_mov_b32_e32 v12, v1
	v_mov_b32_e32 v13, v1
	v_mov_b64_e32 v[32:33], v[14:15]
	s_lshl_b32 s11, s8, 5
	v_bfe_u32 v179, v74, 5, 1
	v_mov_b64_e32 v[30:31], v[12:13]
	v_mov_b64_e32 v[28:29], v[10:11]
	v_mov_b64_e32 v[26:27], v[8:9]
	v_mov_b64_e32 v[24:25], v[6:7]
	v_mov_b64_e32 v[22:23], v[4:5]
	v_mov_b64_e32 v[20:21], v[2:3]
	v_mov_b64_e32 v[18:19], v[0:1]
	v_or_b32_e32 v0, s11, v178
	v_mov_b64_e32 v[2:3], s[4:5]
	v_mad_i64_i32 v[2:3], s[6:7], v0, s33, v[2:3]
	v_lshlrev_b32_e32 v166, 4, v179
	v_mov_b32_e32 v167, v1
	v_lshl_add_u64 v[2:3], v[2:3], 0, v[166:167]
	global_load_dwordx4 v[158:161], v[2:3], off
	global_load_dwordx4 v[154:157], v[2:3], off offset:32
	global_load_dwordx4 v[150:153], v[2:3], off offset:64
	global_load_dwordx4 v[146:149], v[2:3], off offset:96
	global_load_dwordx4 v[142:145], v[2:3], off offset:128
	global_load_dwordx4 v[138:141], v[2:3], off offset:160
	global_load_dwordx4 v[134:137], v[2:3], off offset:192
	global_load_dwordx4 v[130:133], v[2:3], off offset:224
	v_lshlrev_b32_e32 v0, 4, v74
	v_lshlrev_b32_e32 v13, 8, v178
	v_and_b32_e32 v70, 0xf0, v0
	v_bitop3_b32 v199, v166, v13, v70 bitop3:0xde
	v_add_u32_e32 v6, 0, v199
	s_waitcnt vmcnt(0)
	s_waitcnt vmcnt(0) lgkmcnt(0)
	s_barrier
	ds_read_b128 v[2:5], v6 offset:49152
	ds_read_b128 v[6:9], v6 offset:57344
	s_waitcnt lgkmcnt(1)
	v_mfma_f32_32x32x16_bf16 v[50:65], v[2:5], v[158:161], v[18:33]
	v_or_b32_e32 v2, 32, v166
	v_bitop3_b32 v198, v2, v13, v70 bitop3:0xde
	v_lshlrev_b32_e32 v74, 1, v74
	v_and_b32_e32 v74, 32, v74
	s_movk_i32 s6, 0xc0
	v_and_or_b32 v0, v0, s6, v74
	s_cmp_lg_u32 0, -1
	s_waitcnt lgkmcnt(0)
	v_mfma_f32_32x32x16_bf16 v[34:49], v[6:9], v[158:161], v[18:33]
	v_add_u32_e32 v6, 0, v198
	ds_read_b128 v[2:5], v6 offset:49152
	ds_read_b128 v[6:9], v6 offset:57344
	s_cselect_b32 s6, 0, 0
	s_mul_i32 s8, s8, 0xc000
	s_mov_b32 s17, 2
	s_mov_b32 s16, 1
	s_mov_b32 s23, 0
	s_waitcnt lgkmcnt(1)
	v_mfma_f32_32x32x16_bf16 v[50:65], v[2:5], v[154:157], v[50:65]
	v_or_b32_e32 v2, 64, v166
	v_bitop3_b32 v197, v2, v13, v70 bitop3:0xde
	s_mov_b32 s18, -1
	v_lshl_add_u32 v167, v178, 2, s10
	v_mov_b32_e32 v169, v1
	v_mov_b32_e32 v171, v1
	v_mov_b32_e32 v180, 0
	s_waitcnt lgkmcnt(0)
	v_mfma_f32_32x32x16_bf16 v[34:49], v[6:9], v[154:157], v[34:49]
	v_add_u32_e32 v6, 0, v197
	ds_read_b128 v[2:5], v6 offset:49152
	ds_read_b128 v[6:9], v6 offset:57344
	v_mov_b32_e32 v200, 1.0
	s_waitcnt lgkmcnt(1)
	v_mfma_f32_32x32x16_bf16 v[50:65], v[2:5], v[150:153], v[50:65]
	v_or_b32_e32 v2, 0x60, v166
	v_bitop3_b32 v196, v2, v13, v70 bitop3:0xde
	s_waitcnt lgkmcnt(0)
	v_mfma_f32_32x32x16_bf16 v[34:49], v[6:9], v[150:153], v[34:49]
	v_add_u32_e32 v6, 0, v196
	ds_read_b128 v[2:5], v6 offset:49152
	ds_read_b128 v[6:9], v6 offset:57344
	s_waitcnt lgkmcnt(1)
	v_mfma_f32_32x32x16_bf16 v[50:65], v[2:5], v[146:149], v[50:65]
	v_or_b32_e32 v2, 0x80, v166
	v_bitop3_b32 v195, v2, v13, v70 bitop3:0xde
	s_waitcnt lgkmcnt(0)
; __device__ __forceinline__ float max3f(float a, float b, float c) { return __builtin_fmaxf(__builtin_fmaxf(a, b), c); }
; template <bool FIRST, bool MLA>
; __device__ __forceinline__ void partialSM(f32x16& p0, f32x16& p1, f32x16& negm, float& m_reg, float& alpha) {
;   float a = max3f(p0[0], p0[1], p1[0]), b = max3f(p0[2], p0[3], p1[1]); a = max3f(a, p1[2], p1[3]);
; #pragma unroll
;   for (int r = 4; r < 16; r += 4) { a = max3f(a, p0[r], p0[r + 1]); b = max3f(b, p0[r + 2], p0[r + 3]); a = max3f(a, p1[r], p1[r + 1]); b = max3f(b, p1[r + 2], p1[r + 3]); }
;   float pmax = fmaxf(a, b);
;   { auto rr = __builtin_amdgcn_permlane32_swap(__float_as_uint(pmax), __float_as_uint(pmax), false, false);
;     pmax = fmaxf(__uint_as_float(rr[0]), __uint_as_float(rr[1])); }
;   alpha = 1.f;
;   if constexpr (MLA) {
;     if (FIRST) m_reg = pmax;
;     else if (!__builtin_expect(__all(pmax - m_reg <= THR2), 1)) { const float mn = fmaxf(m_reg, pmax); alpha = __builtin_amdgcn_exp2f(m_reg - mn); m_reg = mn; }
; #pragma unroll
;     for (int r = 0; r < 16; ++r) { p0[r] -= m_reg; p1[r] -= m_reg; }
;   } else
;   if (FIRST || __builtin_expect(__any(pmax > THR2), 0)) {
;     const float d = FIRST ? pmax : fmaxf(pmax, 0.f);
; #pragma unroll
;     for (int r = 0; r < 16; ++r) { p0[r] -= d; p1[r] -= d; }
; #pragma unroll
;     for (int r = 0; r < 16; ++r) negm[r] -= d;
;     asm volatile("" : "+v"(negm));
;     if (!FIRST) alpha = __builtin_amdgcn_exp2f(-d);
;   }
; #pragma unroll
;   for (int r = 0; r < 16; ++r) p0[r] = __builtin_amdgcn_exp2f(p0[r]);
; }
; template <bool MLA>
; __device__ __forceinline__ void qkt(f32x16& p0, f32x16& p1, const char* Ks, const char* KRs, const bf16x8* qr, const char* qrl, const f32x16& negm, int r32, int hi) {
;     ...
;   for (int d0 = 0; d0 < 8; ++d0) { int cb = (d0 * 16 + hi * 8) * 2;
;     bf16x8 b0 = *reinterpret_cast<const bf16x8*>(Ks + KSWZ(r32, cb));
;     bf16x8 b1 = *reinterpret_cast<const bf16x8*>(Ks + KSWZ(32 + r32, cb));
;     if (d0 == 0) { p0 = __builtin_amdgcn_mfma_f32_32x32x16_bf16(b0, qr[0], negm, 0, 0, 0); p1 = __builtin_amdgcn_mfma_f32_32x32x16_bf16(b1, qr[0], negm, 0, 0, 0); }
;     else { p0 = __builtin_amdgcn_mfma_f32_32x32x16_bf16(b0, qr[d0], p0, 0, 0, 0); p1 = __builtin_amdgcn_mfma_f32_32x32x16_bf16(b1, qr[d0], p1, 0, 0, 0); } }
	v_mfma_f32_32x32x16_bf16 v[34:49], v[6:9], v[146:149], v[34:49]
	v_add_u32_e32 v6, 0, v195
	ds_read_b128 v[2:5], v6 offset:49152
	ds_read_b128 v[6:9], v6 offset:57344
	s_waitcnt lgkmcnt(1)
	v_mfma_f32_32x32x16_bf16 v[50:65], v[2:5], v[142:145], v[50:65]
	v_or_b32_e32 v2, 0xa0, v166
	v_bitop3_b32 v183, v2, v13, v70 bitop3:0xde
	s_waitcnt lgkmcnt(0)
	v_mfma_f32_32x32x16_bf16 v[34:49], v[6:9], v[142:145], v[34:49]
	v_add_u32_e32 v6, 0, v183
	ds_read_b128 v[2:5], v6 offset:49152
	ds_read_b128 v[6:9], v6 offset:57344
	s_waitcnt lgkmcnt(1)
	v_mfma_f32_32x32x16_bf16 v[50:65], v[2:5], v[138:141], v[50:65]
	v_or_b32_e32 v4, 0xc0, v166
	v_bitop3_b32 v193, v4, v13, v70 bitop3:0xde
	v_add_u32_e32 v4, 0, v193
	ds_read_b128 v[14:17], v4 offset:57344
	ds_read_b128 v[66:69], v4 offset:49152
	v_mov_b32_e32 v2, v1
	v_mov_b32_e32 v3, v1
	v_mov_b32_e32 v4, v1
	s_waitcnt lgkmcnt(2)
	v_mfma_f32_32x32x16_bf16 v[34:49], v[6:9], v[138:141], v[34:49]
	v_mov_b32_e32 v5, v1
	v_mov_b32_e32 v6, v1
	v_mov_b32_e32 v7, v1
	v_mov_b32_e32 v8, v1
	v_mov_b32_e32 v9, v1
	s_waitcnt lgkmcnt(0)
	v_mfma_f32_32x32x16_bf16 v[50:65], v[66:69], v[134:137], v[50:65]
	v_or_b32_e32 v66, 0xe0, v166
	v_bitop3_b32 v194, v66, v13, v70 bitop3:0xde
	v_add_u32_e32 v13, 0, v194
	ds_read_b128 v[66:69], v13 offset:57344
	ds_read_b128 v[70:73], v13 offset:49152
	v_mov_b32_e32 v13, v1
	v_mfma_f32_32x32x16_bf16 v[34:49], v[14:17], v[134:137], v[34:49]
	v_mov_b32_e32 v16, v1
	v_mov_b32_e32 v17, v1
	v_mov_b32_e32 v14, v1
	v_mov_b32_e32 v15, v1
	s_waitcnt lgkmcnt(0)
	v_mfma_f32_32x32x16_bf16 v[50:65], v[70:73], v[130:133], v[50:65]
	v_and_b32_e32 v70, 0x100, v75
	v_or3_b32 v181, v0, v70, v103
	v_add_u32_e32 v182, s6, v181
	v_cmp_gt_u32_e64 s[6:7], 32, v98
	v_mfma_f32_32x32x16_bf16 v[34:49], v[66:69], v[130:133], v[34:49]
	s_nop 6
	v_max_f32_e32 v0, v51, v51
	v_max_f32_e32 v66, v50, v50
	v_max_f32_e32 v0, v66, v0
	s_nop 1
	v_max3_f32 v66, v52, v53, v35
	v_max3_f32 v0, v0, v34, v36
	v_max3_f32 v0, v0, v37, v54
	v_max3_f32 v66, v66, v56, v57
	v_max3_f32 v0, v0, v55, v38
	v_max3_f32 v66, v66, v40, v41
	v_max3_f32 v0, v0, v39, v58
	v_max3_f32 v66, v66, v60, v61
	v_max3_f32 v0, v0, v59, v42
	v_max3_f32 v66, v66, v44, v45
	v_max3_f32 v0, v0, v43, v62
	v_max3_f32 v66, v66, v64, v65
	v_max3_f32 v0, v0, v63, v46
	v_max3_f32 v66, v66, v48, v49
	v_max3_f32 v0, v0, v47, v66
	v_mov_b32_e32 v66, v0
	s_nop 1
	v_permlane32_swap_b32_e32 v0, v66
	v_max_f32_e32 v66, v66, v66
	v_max_f32_e32 v0, v0, v0
	v_max_f32_e32 v0, v0, v66
	v_sub_f32_e32 v50, v50, v0
	v_sub_f32_e32 v51, v51, v0
	v_sub_f32_e32 v52, v52, v0
	v_sub_f32_e32 v53, v53, v0
	v_sub_f32_e32 v54, v54, v0
	v_sub_f32_e32 v55, v55, v0
	v_sub_f32_e32 v56, v56, v0
	v_sub_f32_e32 v57, v57, v0
	v_sub_f32_e32 v58, v58, v0
	v_sub_f32_e32 v59, v59, v0
	v_sub_f32_e32 v60, v60, v0
	v_sub_f32_e32 v61, v61, v0
	v_sub_f32_e32 v62, v62, v0
	v_sub_f32_e32 v63, v63, v0
	v_sub_f32_e32 v64, v64, v0
	v_sub_f32_e32 v65, v65, v0
	v_sub_f32_e32 v97, v49, v0
	v_sub_f32_e32 v96, v48, v0
	v_sub_f32_e32 v95, v47, v0
	v_sub_f32_e32 v94, v46, v0
	v_sub_f32_e32 v93, v45, v0
	v_sub_f32_e32 v92, v44, v0
	v_sub_f32_e32 v91, v43, v0
	v_sub_f32_e32 v90, v42, v0
	v_sub_f32_e32 v89, v41, v0
	v_sub_f32_e32 v88, v40, v0
	v_sub_f32_e32 v87, v39, v0
	v_sub_f32_e32 v86, v38, v0
	v_sub_f32_e32 v85, v37, v0
	v_sub_f32_e32 v84, v36, v0
	v_sub_f32_e32 v83, v35, v0
	v_sub_f32_e32 v82, v34, v0
	v_sub_f32_e32 v81, v33, v0
	v_sub_f32_e32 v80, v32, v0
	v_sub_f32_e32 v79, v31, v0
	v_sub_f32_e32 v78, v30, v0
	v_sub_f32_e32 v77, v29, v0
	v_sub_f32_e32 v76, v28, v0
	v_sub_f32_e32 v75, v27, v0
	v_sub_f32_e32 v74, v26, v0
	v_sub_f32_e32 v73, v25, v0
	v_sub_f32_e32 v72, v24, v0
	v_sub_f32_e32 v71, v23, v0
	v_sub_f32_e32 v70, v22, v0
	v_sub_f32_e32 v69, v21, v0
	v_sub_f32_e32 v68, v20, v0
	v_sub_f32_e32 v67, v19, v0
	v_sub_f32_e32 v66, v18, v0
	v_or_b32_e32 v0, s9, v101
	s_and_b32 s9, s13, 4
	s_lshl_b32 s9, s9, 6
	s_or_b32 s2, s2, s9
	s_add_u32 s2, s98, s2
	v_mov_b32_e32 v18, s8
	s_addc_u32 s3, s99, s3
	v_mad_u32_u24 v18, v99, s33, v18
	s_addk_i32 s8, 0x6000
	v_exp_f32_e32 v217, v50
	v_exp_f32_e32 v219, v51
	v_exp_f32_e32 v215, v52
	v_exp_f32_e32 v218, v53
	v_exp_f32_e32 v214, v54
	v_exp_f32_e32 v216, v55
	v_exp_f32_e32 v212, v56
	v_exp_f32_e32 v213, v57
	v_exp_f32_e32 v209, v58
	v_exp_f32_e32 v211, v59
	v_exp_f32_e32 v208, v60
	v_exp_f32_e32 v210, v61
	v_exp_f32_e32 v205, v62
	v_exp_f32_e32 v207, v63
	v_exp_f32_e32 v204, v64
	v_exp_f32_e32 v206, v65
	v_or3_b32 v0, v0, s19, v100
	v_or_b32_e32 v168, v18, v104
	v_mov_b32_e32 v18, s8
	v_mul_lo_u32 v0, v0, s26
	v_mad_u32_u24 v18, v99, s33, v18
	v_or3_b32 v0, v0, v102, v103
	v_or_b32_e32 v170, v18, v105
	v_mov_b64_e32 v[64:65], v[16:17]
	v_mov_b64_e32 v[48:49], v[16:17]
	v_mov_b64_e32 v[32:33], v[16:17]
	v_lshlrev_b32_e32 v0, 1, v0
	v_mov_b64_e32 v[62:63], v[14:15]
	v_mov_b64_e32 v[60:61], v[12:13]
	v_mov_b64_e32 v[58:59], v[10:11]
	v_mov_b64_e32 v[56:57], v[8:9]
	v_mov_b64_e32 v[54:55], v[6:7]
	v_mov_b64_e32 v[52:53], v[4:5]
	v_mov_b64_e32 v[50:51], v[2:3]
	v_mov_b64_e32 v[46:47], v[14:15]
	v_mov_b64_e32 v[44:45], v[12:13]
	v_mov_b64_e32 v[42:43], v[10:11]
	v_mov_b64_e32 v[40:41], v[8:9]
	v_mov_b64_e32 v[38:39], v[6:7]
	v_mov_b64_e32 v[36:37], v[4:5]
	v_mov_b64_e32 v[34:35], v[2:3]
	v_mov_b64_e32 v[30:31], v[14:15]
	v_mov_b64_e32 v[28:29], v[12:13]
	v_mov_b64_e32 v[26:27], v[10:11]
	v_mov_b64_e32 v[24:25], v[8:9]
	v_mov_b64_e32 v[22:23], v[6:7]
	v_mov_b64_e32 v[20:21], v[4:5]
	v_mov_b64_e32 v[18:19], v[2:3]
